# merge stream: three LDS tile buffers, next tile's LDS fragment reads and LDS stores interleaved between the MFMAs of the current tile
# speedup vs baseline: 1.0207x; 1.0028x over previous
; DI f32x16 mfma(bf16x8 a, bf16x8 b, f32x16 c) { return __builtin_amdgcn_mfma_f32_32x32x16_bf16(a, b, c, 0, 0, 0); }
; template <bool RFA, bool RFB, class LA, class LB, class EPI>
; DI void gemm_tile2s(u16* smem, int nk, LA la, LB lb, EPI epi) {
;   const int tid = tidx(), lane = tid & 63, wave = tid >> 6;
;   const int wm = wave >> 2, wn = wave & 3, lr = lane & 31, lh = lane >> 5;
;   u16* As = smem;
;   u16* Bs = smem + 2 * TILE_ELEMS;
;   f32x16 acc[2];
;   acc[0] = zero16(); acc[1] = zero16();
;   u32x4 ra0[2], rb0[2], ra1[2], rb1[2];
;   auto ld = [&](u32x4 (&ra)[2], u32x4 (&rb)[2], int kt) __attribute__((always_inline)) {
;     const int k0 = kt * 64;
; #pragma unroll
;     for (int i = 0; i < 2; ++i) { const int c = tid + NTH * i; ra[i] = la(A_ROW(c), k0 + A_KC(c) * 8); rb[i] = lb(B_ROW(c), k0 + B_KC(c) * 8); }
;   };
;   auto stl = [&](u32x4 (&ra)[2], u32x4 (&rb)[2], int buf) __attribute__((always_inline)) {
; #pragma unroll
;     for (int i = 0; i < 2; ++i) {
;       const int c = tid + NTH * i;
;       *(u32x4*)(As + buf * TILE_ELEMS + A_ROW(c) * LDT + A_KC(c) * 8) = ra[i];
;       *(u32x4*)(Bs + buf * TILE_ELEMS + B_ROW(c) * LDT + B_KC(c) * 8) = rb[i];
;     }
;   };
;   auto compute = [&](int buf) __attribute__((always_inline)) {
;     const u16* Ab = As + buf * TILE_ELEMS + (wm * 64 + lr) * LDT + lh * 8;
;     const u16* Bb = Bs + buf * TILE_ELEMS + (wn * 32 + lr) * LDT + lh * 8;
; #pragma unroll
;     for (int ks = 0; ks < 4; ++ks) {
;       const bf16x8 a0 = *(const bf16x8*)(Ab + ks * 16);
;       const bf16x8 a1 = *(const bf16x8*)(Ab + 32 * LDT + ks * 16);
;       const bf16x8 b = *(const bf16x8*)(Bb + ks * 16);
;       acc[0] = mfma(a0, b, acc[0]);
;       acc[1] = mfma(a1, b, acc[1]);
;     }
;   };
;   ld(ra0, rb0, 0);
;   if (nk > 1) ld(ra1, rb1, 1);
;   stl(ra0, rb0, 0);
;   if (nk > 2) ld(ra0, rb0, 2);
;   __syncthreads();
; DI void phase_merge(const Prm& p, u16* smem, int l, int& base) {
;   TASK_LOOP(t, 8 * 128, base) {
;     const int tn = t & 7, tm = t >> 3, n0 = tn * 128, m0 = tm * 128;
;     f32x16 macc[2];
;     macc[0] = zero16(); macc[1] = zero16();
;     merge_branch(p, smem, p.PaT + (size_t)l * 1024 * 768, p.UT, 768, 0, n0, m0, macc);
;     merge_branch(p, smem, p.PbT + (size_t)l * 1024 * 128, p.ob, 128, 1, n0, m0, macc);
;     ...
;     merge_branch(p, smem, p.PdT + (size_t)l * 1024 * 256, p.od, 256, 3, n0, m0, macc);
.LBB0_2250:
	v_readlane_b32 s36, v253, 28
	v_readlane_b32 s37, v253, 29
	v_readlane_b32 s38, v253, 30
	v_readlane_b32 s39, v253, 31
	v_readlane_b32 s40, v252, 4
	v_readlane_b32 s41, v252, 5
	v_readlane_b32 s42, v252, 6
	v_readlane_b32 s43, v252, 7
	v_readlane_b32 s48, v253, 20
	v_readlane_b32 s49, v253, 21
	v_and_b32_e32 v226, 7, v224
	v_lshlrev_b32_e32 v226, 4, v226
	v_lshrrev_b32_e32 v227, 3, v224
	v_and_b32_e32 v228, 0xffffffe3, v227
	v_lshrrev_b32_e32 v229, 1, v227
	v_and_b32_e32 v229, 12, v229
	v_or_b32_e32 v228, v228, v229
	v_lshlrev_b32_e32 v229, 2, v227
	v_and_b32_e32 v229, 16, v229
	v_or_b32_e32 v228, v228, v229
	s_movk_i32 s52, 0x600
	v_mad_u32_u24 v210, v228, s52, v226
	v_mad_u32_u24 v214, v227, s52, v226
	s_movk_i32 s52, 0x100
	v_mad_u32_u24 v211, v228, s52, v226
	v_mad_u32_u24 v215, v227, s52, v226
	s_movk_i32 s52, 0x300
	v_mad_u32_u24 v212, v228, s52, v226
	v_mad_u32_u24 v216, v227, s52, v226
	s_movk_i32 s52, 0x200
	v_mad_u32_u24 v213, v228, s52, v226
	v_mad_u32_u24 v217, v227, s52, v226
	s_movk_i32 s52, 0x90
	v_mad_u32_u24 v218, v227, s52, v226
	v_lshrrev_b32_e32 v226, 1, v224
	v_and_b32_e32 v227, 16, v226
	v_and_b32_e32 v228, 31, v224
	v_lshrrev_b32_e32 v229, 2, v224
	v_and_b32_e32 v229, 64, v229
	v_and_b32_e32 v226, 0x60, v226
	v_or_b32_e32 v226, v226, v228
	v_or_b32_e32 v228, v229, v228
	v_mad_u32_u24 v219, v228, s52, v227
	v_mad_u32_u24 v220, v226, s52, v227
	v_add_u32_e32 v220, 0xd800, v220
	v_add_u32_e32 v223, 0xd800, v218
	v_or_b32_e32 v229, v229, v227
	v_lshlrev_b32_e32 v229, 1, v229
	v_lshl_add_u32 v221, v226, 13, v229
	v_lshl_add_u32 v222, v226, 11, v229
	s_and_b32 s58, s31, 7
	s_lshl_b32 s58, s58, 7
	s_lshr_b32 s59, s31, 3
	s_lshl_b32 s59, s59, 7
	s_mul_i32 s52, s58, 0x600
	s_add_u32 s0, s16, s52
	s_addc_u32 s1, s17, 0
	s_add_u32 s2, s0, 0x18000
	s_addc_u32 s3, s1, 0
	s_mul_i32 s52, s59, 0x600
	s_add_u32 s4, s14, s52
	s_addc_u32 s5, s15, 0
	s_add_u32 s6, s4, 0x18000
	s_addc_u32 s7, s5, 0
	global_load_dwordx4 v[66:69], v210, s[0:1]
	global_load_dwordx4 v[70:73], v210, s[2:3]
	global_load_dwordx4 v[74:77], v214, s[4:5]
	global_load_dwordx4 v[78:81], v214, s[6:7]
	global_load_dwordx4 v[82:85], v210, s[0:1] offset:128
	global_load_dwordx4 v[86:89], v210, s[2:3] offset:128
	global_load_dwordx4 v[90:93], v214, s[4:5] offset:128
	global_load_dwordx4 v[94:97], v214, s[6:7] offset:128
	global_load_dwordx4 v[98:101], v210, s[0:1] offset:256
	global_load_dwordx4 v[102:105], v210, s[2:3] offset:256
	global_load_dwordx4 v[106:109], v214, s[4:5] offset:256
	global_load_dwordx4 v[110:113], v214, s[6:7] offset:256
	global_load_dwordx4 v[114:117], v210, s[0:1] offset:384
	global_load_dwordx4 v[118:121], v210, s[2:3] offset:384
	global_load_dwordx4 v[122:125], v214, s[4:5] offset:384
	global_load_dwordx4 v[126:129], v214, s[6:7] offset:384
	s_waitcnt vmcnt(8)
	ds_write_b128 v218, v[66:69]
	ds_write_b128 v218, v[70:73] offset:9216
	ds_write_b128 v223, v[74:77]
	ds_write_b128 v223, v[78:81] offset:9216
	ds_write_b128 v218, v[82:85] offset:18432
	ds_write_b128 v218, v[86:89] offset:27648
	ds_write_b128 v223, v[90:93] offset:18432
	ds_write_b128 v223, v[94:97] offset:27648
	global_load_dwordx4 v[66:69], v210, s[0:1] offset:512
	global_load_dwordx4 v[70:73], v210, s[2:3] offset:512
	global_load_dwordx4 v[74:77], v214, s[4:5] offset:512
	global_load_dwordx4 v[78:81], v214, s[6:7] offset:512
	global_load_dwordx4 v[82:85], v210, s[0:1] offset:640
	global_load_dwordx4 v[86:89], v210, s[2:3] offset:640
	global_load_dwordx4 v[90:93], v214, s[4:5] offset:640
	global_load_dwordx4 v[94:97], v214, s[6:7] offset:640
	s_waitcnt vmcnt(0)
	s_waitcnt lgkmcnt(0)
	s_barrier
	ds_read_b128 v[130:133], v219
	ds_read_b128 v[134:137], v220
	ds_read_b128 v[138:141], v219 offset:4608
	ds_read_b128 v[142:145], v219 offset:32
	ds_read_b128 v[146:149], v220 offset:32
	ds_read_b128 v[150:153], v219 offset:4640
	s_waitcnt lgkmcnt(0)
.Lmrg_task:
	s_lshl_b32 s52, s59, 13
	s_lshl_b32 s53, s58, 1
	s_add_u32 s52, s52, s53
	s_add_u32 s8, s42, s52
	s_addc_u32 s9, s43, 0
	s_add_u32 s10, s8, 0x1000
	s_addc_u32 s11, s9, 0
	s_lshl_b32 s52, s59, 11
	s_add_u32 s52, s52, s53
	s_add_u32 s12, s48, s52
	s_addc_u32 s13, s49, 0
	ds_read_b128 v[154:157], v219 offset:64
	ds_read_b128 v[158:161], v220 offset:64
	ds_read_b128 v[162:165], v219 offset:4672
	v_mfma_f32_32x32x16_bf16 v[18:33], v[130:133], v[134:137], 0
	ds_read_b128 v[166:169], v219 offset:96
	ds_read_b128 v[170:173], v220 offset:96
	ds_read_b128 v[174:177], v219 offset:4704
	v_mfma_f32_32x32x16_bf16 v[2:17], v[138:141], v[134:137], 0
	s_waitcnt vmcnt(16)
	ds_write_b128 v218, v[98:101] offset:36864
	ds_write_b128 v218, v[102:105] offset:46080
	v_mfma_f32_32x32x16_bf16 v[18:33], v[142:145], v[146:149], v[18:33]
	ds_write_b128 v223, v[106:109] offset:36864
	ds_write_b128 v223, v[110:113] offset:46080
	v_mfma_f32_32x32x16_bf16 v[2:17], v[150:153], v[146:149], v[2:17]
	global_load_dwordx4 v[98:101], v210, s[0:1] offset:768
	global_load_dwordx4 v[102:105], v210, s[2:3] offset:768
	global_load_dwordx4 v[106:109], v214, s[4:5] offset:768
	global_load_dwordx4 v[110:113], v214, s[6:7] offset:768
	ds_read_b128 v[130:133], v219 offset:18432
	ds_read_b128 v[134:137], v220 offset:18432
	ds_read_b128 v[138:141], v219 offset:23040
	s_waitcnt lgkmcnt(11)
	v_mfma_f32_32x32x16_bf16 v[18:33], v[154:157], v[158:161], v[18:33]
	ds_read_b128 v[142:145], v219 offset:18464
	ds_read_b128 v[146:149], v220 offset:18464
	ds_read_b128 v[150:153], v219 offset:23072
	s_waitcnt lgkmcnt(13)
	v_mfma_f32_32x32x16_bf16 v[2:17], v[162:165], v[158:161], v[2:17]
	s_waitcnt lgkmcnt(11)
	v_mfma_f32_32x32x16_bf16 v[18:33], v[166:169], v[170:173], v[18:33]
	s_waitcnt lgkmcnt(10)
	v_mfma_f32_32x32x16_bf16 v[2:17], v[174:177], v[170:173], v[2:17]
	s_waitcnt lgkmcnt(0)
	s_barrier
; DI f32x16 mfma(bf16x8 a, bf16x8 b, f32x16 c) { return __builtin_amdgcn_mfma_f32_32x32x16_bf16(a, b, c, 0, 0, 0); }
; template <bool RFA, bool RFB, class LA, class LB, class EPI>
; DI void gemm_tile2s(u16* smem, int nk, LA la, LB lb, EPI epi) {
;     ...
;   auto compute = [&](int buf) __attribute__((always_inline)) {
;     const u16* Ab = As + buf * TILE_ELEMS + (wm * 64 + lr) * LDT + lh * 8;
;     const u16* Bb = Bs + buf * TILE_ELEMS + (wn * 32 + lr) * LDT + lh * 8;
; #pragma unroll
;     for (int ks = 0; ks < 4; ++ks) {
;       const bf16x8 a0 = *(const bf16x8*)(Ab + ks * 16);
;       const bf16x8 a1 = *(const bf16x8*)(Ab + 32 * LDT + ks * 16);
;       const bf16x8 b = *(const bf16x8*)(Bb + ks * 16);
;       acc[0] = mfma(a0, b, acc[0]);
;       acc[1] = mfma(a1, b, acc[1]);
;     }
;   };
;     ...
;     if (kt + 1 < nk) { stl(ra1, rb1, 1); if (kt + 3 < nk) ld(ra1, rb1, kt + 3); }
;     __syncthreads();
;     if (kt + 1 < nk) {
;       compute(1);
;       if (kt + 2 < nk) { stl(ra0, rb0, 0); if (kt + 4 < nk) ld(ra0, rb0, kt + 4); }
;       __syncthreads();
	ds_read_b128 v[154:157], v219 offset:18496
	ds_read_b128 v[158:161], v220 offset:18496
	ds_read_b128 v[162:165], v219 offset:23104
	v_mfma_f32_32x32x16_bf16 v[18:33], v[130:133], v[134:137], v[18:33]
	ds_read_b128 v[166:169], v219 offset:18528
	ds_read_b128 v[170:173], v220 offset:18528
	ds_read_b128 v[174:177], v219 offset:23136
	v_mfma_f32_32x32x16_bf16 v[2:17], v[138:141], v[134:137], v[2:17]
	s_waitcnt vmcnt(16)
	ds_write_b128 v218, v[114:117]
	ds_write_b128 v218, v[118:121] offset:9216
	v_mfma_f32_32x32x16_bf16 v[18:33], v[142:145], v[146:149], v[18:33]
	ds_write_b128 v223, v[122:125]
	ds_write_b128 v223, v[126:129] offset:9216
	v_mfma_f32_32x32x16_bf16 v[2:17], v[150:153], v[146:149], v[2:17]
	global_load_dwordx4 v[114:117], v210, s[0:1] offset:896
	global_load_dwordx4 v[118:121], v210, s[2:3] offset:896
	global_load_dwordx4 v[122:125], v214, s[4:5] offset:896
	global_load_dwordx4 v[126:129], v214, s[6:7] offset:896
	ds_read_b128 v[130:133], v219 offset:36864
	ds_read_b128 v[134:137], v220 offset:36864
	ds_read_b128 v[138:141], v219 offset:41472
	s_waitcnt lgkmcnt(11)
	v_mfma_f32_32x32x16_bf16 v[18:33], v[154:157], v[158:161], v[18:33]
	ds_read_b128 v[142:145], v219 offset:36896
	ds_read_b128 v[146:149], v220 offset:36896
	ds_read_b128 v[150:153], v219 offset:41504
	s_waitcnt lgkmcnt(13)
	v_mfma_f32_32x32x16_bf16 v[2:17], v[162:165], v[158:161], v[2:17]
	s_waitcnt lgkmcnt(11)
	v_mfma_f32_32x32x16_bf16 v[18:33], v[166:169], v[170:173], v[18:33]
	s_waitcnt lgkmcnt(10)
	v_mfma_f32_32x32x16_bf16 v[2:17], v[174:177], v[170:173], v[2:17]
	s_waitcnt lgkmcnt(0)
	s_barrier
	ds_read_b128 v[154:157], v219 offset:36928
	ds_read_b128 v[158:161], v220 offset:36928
	ds_read_b128 v[162:165], v219 offset:41536
	v_mfma_f32_32x32x16_bf16 v[18:33], v[130:133], v[134:137], v[18:33]
	ds_read_b128 v[166:169], v219 offset:36960
	ds_read_b128 v[170:173], v220 offset:36960
	ds_read_b128 v[174:177], v219 offset:41568
	v_mfma_f32_32x32x16_bf16 v[2:17], v[138:141], v[134:137], v[2:17]
	s_waitcnt vmcnt(16)
	ds_write_b128 v218, v[66:69] offset:18432
	ds_write_b128 v218, v[70:73] offset:27648
	v_mfma_f32_32x32x16_bf16 v[18:33], v[142:145], v[146:149], v[18:33]
	ds_write_b128 v223, v[74:77] offset:18432
	ds_write_b128 v223, v[78:81] offset:27648
	v_mfma_f32_32x32x16_bf16 v[2:17], v[150:153], v[146:149], v[2:17]
	global_load_dwordx4 v[66:69], v210, s[0:1] offset:1024
	global_load_dwordx4 v[70:73], v210, s[2:3] offset:1024
	global_load_dwordx4 v[74:77], v214, s[4:5] offset:1024
	global_load_dwordx4 v[78:81], v214, s[6:7] offset:1024
	ds_read_b128 v[130:133], v219
	ds_read_b128 v[134:137], v220
	ds_read_b128 v[138:141], v219 offset:4608
	s_waitcnt lgkmcnt(11)
	v_mfma_f32_32x32x16_bf16 v[18:33], v[154:157], v[158:161], v[18:33]
	ds_read_b128 v[142:145], v219 offset:32
	ds_read_b128 v[146:149], v220 offset:32
	ds_read_b128 v[150:153], v219 offset:4640
	s_waitcnt lgkmcnt(13)
	v_mfma_f32_32x32x16_bf16 v[2:17], v[162:165], v[158:161], v[2:17]
	s_waitcnt lgkmcnt(11)
	v_mfma_f32_32x32x16_bf16 v[18:33], v[166:169], v[170:173], v[18:33]
	s_waitcnt lgkmcnt(10)
	v_mfma_f32_32x32x16_bf16 v[2:17], v[174:177], v[170:173], v[2:17]
	s_waitcnt lgkmcnt(0)
	s_barrier
	ds_read_b128 v[154:157], v219 offset:64
	ds_read_b128 v[158:161], v220 offset:64
	ds_read_b128 v[162:165], v219 offset:4672
	v_mfma_f32_32x32x16_bf16 v[18:33], v[130:133], v[134:137], v[18:33]
	ds_read_b128 v[166:169], v219 offset:96
	ds_read_b128 v[170:173], v220 offset:96
	ds_read_b128 v[174:177], v219 offset:4704
	v_mfma_f32_32x32x16_bf16 v[2:17], v[138:141], v[134:137], v[2:17]
	s_waitcnt vmcnt(16)
	ds_write_b128 v218, v[82:85] offset:36864
	ds_write_b128 v218, v[86:89] offset:46080
	v_mfma_f32_32x32x16_bf16 v[18:33], v[142:145], v[146:149], v[18:33]
	ds_write_b128 v223, v[90:93] offset:36864
	ds_write_b128 v223, v[94:97] offset:46080
	v_mfma_f32_32x32x16_bf16 v[2:17], v[150:153], v[146:149], v[2:17]
	global_load_dwordx4 v[82:85], v210, s[0:1] offset:1152
	global_load_dwordx4 v[86:89], v210, s[2:3] offset:1152
	global_load_dwordx4 v[90:93], v214, s[4:5] offset:1152
	global_load_dwordx4 v[94:97], v214, s[6:7] offset:1152
	ds_read_b128 v[130:133], v219 offset:18432
	ds_read_b128 v[134:137], v220 offset:18432
	ds_read_b128 v[138:141], v219 offset:23040
	s_waitcnt lgkmcnt(11)
	v_mfma_f32_32x32x16_bf16 v[18:33], v[154:157], v[158:161], v[18:33]
	ds_read_b128 v[142:145], v219 offset:18464
	ds_read_b128 v[146:149], v220 offset:18464
	ds_read_b128 v[150:153], v219 offset:23072
	s_waitcnt lgkmcnt(13)
	v_mfma_f32_32x32x16_bf16 v[2:17], v[162:165], v[158:161], v[2:17]
	s_waitcnt lgkmcnt(11)
	v_mfma_f32_32x32x16_bf16 v[18:33], v[166:169], v[170:173], v[18:33]
	s_waitcnt lgkmcnt(10)
	v_mfma_f32_32x32x16_bf16 v[2:17], v[174:177], v[170:173], v[2:17]
	s_waitcnt lgkmcnt(0)
	s_barrier
	ds_read_b128 v[154:157], v219 offset:18496
	ds_read_b128 v[158:161], v220 offset:18496
	ds_read_b128 v[162:165], v219 offset:23104
	v_mfma_f32_32x32x16_bf16 v[18:33], v[130:133], v[134:137], v[18:33]
	ds_read_b128 v[166:169], v219 offset:18528
	ds_read_b128 v[170:173], v220 offset:18528
	ds_read_b128 v[174:177], v219 offset:23136
	v_mfma_f32_32x32x16_bf16 v[2:17], v[138:141], v[134:137], v[2:17]
	s_waitcnt vmcnt(12)
	ds_write_b128 v218, v[98:101]
	ds_write_b128 v218, v[102:105] offset:9216
	v_mfma_f32_32x32x16_bf16 v[18:33], v[142:145], v[146:149], v[18:33]
	ds_write_b128 v223, v[106:109]
	ds_write_b128 v223, v[110:113] offset:9216
	v_mfma_f32_32x32x16_bf16 v[2:17], v[150:153], v[146:149], v[2:17]
	global_load_dwordx4 v[98:101], v210, s[0:1] offset:1280
	global_load_dwordx4 v[102:105], v210, s[2:3] offset:1280
	global_load_dwordx4 v[106:109], v214, s[4:5] offset:1280
	global_load_dwordx4 v[110:113], v214, s[6:7] offset:1280
	ds_read_b128 v[130:133], v219 offset:36864
	ds_read_b128 v[134:137], v220 offset:36864
	ds_read_b128 v[138:141], v219 offset:41472
	s_waitcnt lgkmcnt(11)
	v_mfma_f32_32x32x16_bf16 v[18:33], v[154:157], v[158:161], v[18:33]
	ds_read_b128 v[142:145], v219 offset:36896
	ds_read_b128 v[146:149], v220 offset:36896
	ds_read_b128 v[150:153], v219 offset:41504
	s_waitcnt lgkmcnt(13)
	v_mfma_f32_32x32x16_bf16 v[2:17], v[162:165], v[158:161], v[2:17]
	s_waitcnt lgkmcnt(11)
	v_mfma_f32_32x32x16_bf16 v[18:33], v[166:169], v[170:173], v[18:33]
	s_waitcnt lgkmcnt(10)
	v_mfma_f32_32x32x16_bf16 v[2:17], v[174:177], v[170:173], v[2:17]
	s_waitcnt lgkmcnt(0)
	s_barrier
; DI float bflo(unsigned w) { return __uint_as_float(w << 16); }
; DI float bfhi(unsigned w) { return __uint_as_float(w & 0xffff0000u); }
; template <class ACC>
; DI void merge_branch(const Prm& p, u16* smem, const u16* W, const u16* X, int ld, int bi, int n0, int m0, ACC& macc) {
;   auto la = [&](int row, int k) __attribute__((always_inline)) { return *(const u32x4*)(W + (size_t)(n0 + (row & ~31) + perm_m(row & 31)) * ld + k); };
;   auto lb = [&](int row, int k) __attribute__((always_inline)) { return *(const u32x4*)(X + (size_t)(m0 + row) * ld + k); };
;   auto epi = [&](f32x16 (&acc)[2], int wm, int wn, int lane) __attribute__((always_inline)) {
;     const int lr = lane & 31, lh = lane >> 5;
;     const int tok = m0 + wn * 32 + lr;
; #pragma unroll
;     for (int i = 0; i < 2; ++i)
; #pragma unroll
;       for (int h2 = 0; h2 < 2; ++h2) {
;         const int n = n0 + wm * 64 + i * 32 + 16 * lh + 8 * h2;
;         const u32x4 gz = *(const u32x4*)(p.zg + (size_t)tok * 4096 + bi * 1024 + n);
; #pragma unroll
;         for (int e = 0; e < 4; ++e) {
;           macc[i][8 * h2 + 2 * e] += bflo(gz[e]) * acc[i][8 * h2 + 2 * e];
;           macc[i][8 * h2 + 2 * e + 1] += bfhi(gz[e]) * acc[i][8 * h2 + 2 * e + 1];
;         }
;       }
;   };
;   gemm_tile2s<false, false>(smem, ld >> 6, la, lb, epi);
; DI void phase_merge(const Prm& p, u16* smem, int l, int& base) {
;     ...
;     merge_branch(p, smem, p.PaT + (size_t)l * 1024 * 768, p.UT, 768, 0, n0, m0, macc);
;     merge_branch(p, smem, p.PbT + (size_t)l * 1024 * 128, p.ob, 128, 1, n0, m0, macc);
	ds_read_b128 v[154:157], v219 offset:36928
	ds_read_b128 v[158:161], v220 offset:36928
	ds_read_b128 v[162:165], v219 offset:41536
	v_mfma_f32_32x32x16_bf16 v[18:33], v[130:133], v[134:137], v[18:33]
	ds_read_b128 v[166:169], v219 offset:36960
	ds_read_b128 v[170:173], v220 offset:36960
	ds_read_b128 v[174:177], v219 offset:41568
	v_mfma_f32_32x32x16_bf16 v[2:17], v[138:141], v[134:137], v[2:17]
	s_waitcnt vmcnt(12)
	ds_write_b128 v218, v[114:117] offset:18432
	ds_write_b128 v218, v[118:121] offset:27648
	v_mfma_f32_32x32x16_bf16 v[18:33], v[142:145], v[146:149], v[18:33]
	ds_write_b128 v223, v[122:125] offset:18432
	ds_write_b128 v223, v[126:129] offset:27648
	v_mfma_f32_32x32x16_bf16 v[2:17], v[150:153], v[146:149], v[2:17]
	global_load_dwordx4 v[114:117], v210, s[0:1] offset:1408
	global_load_dwordx4 v[118:121], v210, s[2:3] offset:1408
	global_load_dwordx4 v[122:125], v214, s[4:5] offset:1408
	global_load_dwordx4 v[126:129], v214, s[6:7] offset:1408
	global_load_dwordx4 v[178:181], v221, s[8:9]
	global_load_dwordx4 v[182:185], v221, s[8:9] offset:16
	global_load_dwordx4 v[186:189], v221, s[8:9] offset:64
	global_load_dwordx4 v[190:193], v221, s[8:9] offset:80
	ds_read_b128 v[130:133], v219
	ds_read_b128 v[134:137], v220
	ds_read_b128 v[138:141], v219 offset:4608
	s_waitcnt lgkmcnt(11)
	v_mfma_f32_32x32x16_bf16 v[18:33], v[154:157], v[158:161], v[18:33]
	ds_read_b128 v[142:145], v219 offset:32
	ds_read_b128 v[146:149], v220 offset:32
	ds_read_b128 v[150:153], v219 offset:4640
	s_waitcnt lgkmcnt(13)
	v_mfma_f32_32x32x16_bf16 v[2:17], v[162:165], v[158:161], v[2:17]
	s_waitcnt lgkmcnt(11)
	v_mfma_f32_32x32x16_bf16 v[18:33], v[166:169], v[170:173], v[18:33]
	s_waitcnt lgkmcnt(10)
	v_mfma_f32_32x32x16_bf16 v[2:17], v[174:177], v[170:173], v[2:17]
	s_waitcnt lgkmcnt(0)
	s_barrier
	ds_read_b128 v[154:157], v219 offset:64
	ds_read_b128 v[158:161], v220 offset:64
	ds_read_b128 v[162:165], v219 offset:4672
	v_mfma_f32_32x32x16_bf16 v[18:33], v[130:133], v[134:137], v[18:33]
	ds_read_b128 v[166:169], v219 offset:96
	ds_read_b128 v[170:173], v220 offset:96
	ds_read_b128 v[174:177], v219 offset:4704
	v_mfma_f32_32x32x16_bf16 v[2:17], v[138:141], v[134:137], v[2:17]
	s_waitcnt vmcnt(16)
	ds_write_b128 v218, v[66:69] offset:36864
	ds_write_b128 v218, v[70:73] offset:46080
	v_mfma_f32_32x32x16_bf16 v[18:33], v[142:145], v[146:149], v[18:33]
	ds_write_b128 v223, v[74:77] offset:36864
	ds_write_b128 v223, v[78:81] offset:46080
	v_mfma_f32_32x32x16_bf16 v[2:17], v[150:153], v[146:149], v[2:17]
	s_mul_i32 s52, s58, 0x100
	s_add_u32 s0, s20, s52
	s_addc_u32 s1, s21, 0
	s_add_u32 s2, s0, 0x4000
	s_addc_u32 s3, s1, 0
	s_mul_i32 s52, s59, 0x100
	s_add_u32 s4, s36, s52
	s_addc_u32 s5, s37, 0
	s_add_u32 s6, s4, 0x4000
	s_addc_u32 s7, s5, 0
	global_load_dwordx4 v[66:69], v211, s[0:1]
	global_load_dwordx4 v[70:73], v211, s[2:3]
	global_load_dwordx4 v[74:77], v215, s[4:5]
	global_load_dwordx4 v[78:81], v215, s[6:7]
	ds_read_b128 v[130:133], v219 offset:18432
	ds_read_b128 v[134:137], v220 offset:18432
	ds_read_b128 v[138:141], v219 offset:23040
	s_waitcnt lgkmcnt(11)
	v_mfma_f32_32x32x16_bf16 v[18:33], v[154:157], v[158:161], v[18:33]
	ds_read_b128 v[142:145], v219 offset:18464
	ds_read_b128 v[146:149], v220 offset:18464
	ds_read_b128 v[150:153], v219 offset:23072
	s_waitcnt lgkmcnt(13)
	v_mfma_f32_32x32x16_bf16 v[2:17], v[162:165], v[158:161], v[2:17]
	s_waitcnt lgkmcnt(11)
	v_mfma_f32_32x32x16_bf16 v[18:33], v[166:169], v[170:173], v[18:33]
	s_waitcnt lgkmcnt(10)
	v_mfma_f32_32x32x16_bf16 v[2:17], v[174:177], v[170:173], v[2:17]
	s_waitcnt lgkmcnt(0)
	s_barrier
	ds_read_b128 v[154:157], v219 offset:18496
	ds_read_b128 v[158:161], v220 offset:18496
	ds_read_b128 v[162:165], v219 offset:23104
	v_mfma_f32_32x32x16_bf16 v[18:33], v[130:133], v[134:137], v[18:33]
	ds_read_b128 v[166:169], v219 offset:18528
	ds_read_b128 v[170:173], v220 offset:18528
	ds_read_b128 v[174:177], v219 offset:23136
	v_mfma_f32_32x32x16_bf16 v[2:17], v[138:141], v[134:137], v[2:17]
	s_waitcnt vmcnt(16)
	ds_write_b128 v218, v[82:85]
	ds_write_b128 v218, v[86:89] offset:9216
	v_mfma_f32_32x32x16_bf16 v[18:33], v[142:145], v[146:149], v[18:33]
	ds_write_b128 v223, v[90:93]
	ds_write_b128 v223, v[94:97] offset:9216
	v_mfma_f32_32x32x16_bf16 v[2:17], v[150:153], v[146:149], v[2:17]
	global_load_dwordx4 v[82:85], v211, s[0:1] offset:128
	global_load_dwordx4 v[86:89], v211, s[2:3] offset:128
	global_load_dwordx4 v[90:93], v215, s[4:5] offset:128
	global_load_dwordx4 v[94:97], v215, s[6:7] offset:128
	global_load_dwordx4 v[194:197], v221, s[8:9] offset:2048
	global_load_dwordx4 v[198:201], v221, s[8:9] offset:2064
	global_load_dwordx4 v[202:205], v221, s[8:9] offset:2112
	global_load_dwordx4 v[206:209], v221, s[8:9] offset:2128
	ds_read_b128 v[130:133], v219 offset:36864
	ds_read_b128 v[134:137], v220 offset:36864
	ds_read_b128 v[138:141], v219 offset:41472
	s_waitcnt lgkmcnt(11)
	v_mfma_f32_32x32x16_bf16 v[18:33], v[154:157], v[158:161], v[18:33]
	ds_read_b128 v[142:145], v219 offset:36896
	ds_read_b128 v[146:149], v220 offset:36896
	ds_read_b128 v[150:153], v219 offset:41504
	s_waitcnt lgkmcnt(13)
	v_mfma_f32_32x32x16_bf16 v[2:17], v[162:165], v[158:161], v[2:17]
	s_waitcnt lgkmcnt(11)
	v_mfma_f32_32x32x16_bf16 v[18:33], v[166:169], v[170:173], v[18:33]
	s_waitcnt lgkmcnt(10)
	v_mfma_f32_32x32x16_bf16 v[2:17], v[174:177], v[170:173], v[2:17]
	s_waitcnt lgkmcnt(0)
	s_barrier
; DI float bflo(unsigned w) { return __uint_as_float(w << 16); }
; DI float bfhi(unsigned w) { return __uint_as_float(w & 0xffff0000u); }
; template <class ACC>
; DI void merge_branch(const Prm& p, u16* smem, const u16* W, const u16* X, int ld, int bi, int n0, int m0, ACC& macc) {
;   auto la = [&](int row, int k) __attribute__((always_inline)) { return *(const u32x4*)(W + (size_t)(n0 + (row & ~31) + perm_m(row & 31)) * ld + k); };
;   auto lb = [&](int row, int k) __attribute__((always_inline)) { return *(const u32x4*)(X + (size_t)(m0 + row) * ld + k); };
;   auto epi = [&](f32x16 (&acc)[2], int wm, int wn, int lane) __attribute__((always_inline)) {
;     const int lr = lane & 31, lh = lane >> 5;
;     const int tok = m0 + wn * 32 + lr;
; #pragma unroll
;     for (int i = 0; i < 2; ++i)
; #pragma unroll
;       for (int h2 = 0; h2 < 2; ++h2) {
;         const int n = n0 + wm * 64 + i * 32 + 16 * lh + 8 * h2;
;         const u32x4 gz = *(const u32x4*)(p.zg + (size_t)tok * 4096 + bi * 1024 + n);
; #pragma unroll
;         for (int e = 0; e < 4; ++e) {
;           macc[i][8 * h2 + 2 * e] += bflo(gz[e]) * acc[i][8 * h2 + 2 * e];
;           macc[i][8 * h2 + 2 * e + 1] += bfhi(gz[e]) * acc[i][8 * h2 + 2 * e + 1];
;         }
;       }
;   };
;   gemm_tile2s<false, false>(smem, ld >> 6, la, lb, epi);
; DI void phase_merge(const Prm& p, u16* smem, int l, int& base) {
;     ...
;     merge_branch(p, smem, p.PbT + (size_t)l * 1024 * 128, p.ob, 128, 1, n0, m0, macc);
	ds_read_b128 v[154:157], v219 offset:36928
	ds_read_b128 v[158:161], v220 offset:36928
	ds_read_b128 v[162:165], v219 offset:41536
	v_mfma_f32_32x32x16_bf16 v[18:33], v[130:133], v[134:137], v[18:33]
	ds_read_b128 v[166:169], v219 offset:36960
	ds_read_b128 v[170:173], v220 offset:36960
	ds_read_b128 v[174:177], v219 offset:41568
	v_mfma_f32_32x32x16_bf16 v[2:17], v[138:141], v[134:137], v[2:17]
	s_waitcnt vmcnt(20)
	ds_write_b128 v218, v[98:101] offset:18432
	ds_write_b128 v218, v[102:105] offset:27648
	v_mfma_f32_32x32x16_bf16 v[18:33], v[142:145], v[146:149], v[18:33]
	ds_write_b128 v223, v[106:109] offset:18432
	ds_write_b128 v223, v[110:113] offset:27648
	v_mfma_f32_32x32x16_bf16 v[2:17], v[150:153], v[146:149], v[2:17]
	s_mul_i32 s52, s58, 0x300
	s_add_u32 s0, s22, s52
	s_addc_u32 s1, s23, 0
	s_add_u32 s2, s0, 0xc000
	s_addc_u32 s3, s1, 0
	s_mul_i32 s52, s59, 0x300
	s_add_u32 s4, s38, s52
	s_addc_u32 s5, s39, 0
	s_add_u32 s6, s4, 0xc000
	s_addc_u32 s7, s5, 0
	global_load_dwordx4 v[98:101], v212, s[0:1]
	global_load_dwordx4 v[102:105], v212, s[2:3]
	global_load_dwordx4 v[106:109], v216, s[4:5]
	global_load_dwordx4 v[110:113], v216, s[6:7]
	ds_read_b128 v[130:133], v219
	ds_read_b128 v[134:137], v220
	ds_read_b128 v[138:141], v219 offset:4608
	s_waitcnt lgkmcnt(11)
	v_mfma_f32_32x32x16_bf16 v[18:33], v[154:157], v[158:161], v[18:33]
	ds_read_b128 v[142:145], v219 offset:32
	ds_read_b128 v[146:149], v220 offset:32
	ds_read_b128 v[150:153], v219 offset:4640
	s_waitcnt lgkmcnt(13)
	v_mfma_f32_32x32x16_bf16 v[2:17], v[162:165], v[158:161], v[2:17]
	s_waitcnt lgkmcnt(11)
	v_mfma_f32_32x32x16_bf16 v[18:33], v[166:169], v[170:173], v[18:33]
	s_waitcnt lgkmcnt(10)
	v_mfma_f32_32x32x16_bf16 v[2:17], v[174:177], v[170:173], v[2:17]
	s_waitcnt lgkmcnt(0)
	s_barrier
	ds_read_b128 v[154:157], v219 offset:64
	ds_read_b128 v[158:161], v220 offset:64
	ds_read_b128 v[162:165], v219 offset:4672
	v_mfma_f32_32x32x16_bf16 v[18:33], v[130:133], v[134:137], v[18:33]
	ds_read_b128 v[166:169], v219 offset:96
	ds_read_b128 v[170:173], v220 offset:96
	ds_read_b128 v[174:177], v219 offset:4704
	v_mfma_f32_32x32x16_bf16 v[2:17], v[138:141], v[134:137], v[2:17]
	s_waitcnt vmcnt(20)
	ds_write_b128 v218, v[114:117] offset:36864
	ds_write_b128 v218, v[118:121] offset:46080
	v_mfma_f32_32x32x16_bf16 v[18:33], v[142:145], v[146:149], v[18:33]
	ds_write_b128 v223, v[122:125] offset:36864
	ds_write_b128 v223, v[126:129] offset:46080
	v_mfma_f32_32x32x16_bf16 v[2:17], v[150:153], v[146:149], v[2:17]
	global_load_dwordx4 v[114:117], v212, s[0:1] offset:128
	global_load_dwordx4 v[118:121], v212, s[2:3] offset:128
	global_load_dwordx4 v[122:125], v216, s[4:5] offset:128
	global_load_dwordx4 v[126:129], v216, s[6:7] offset:128
	ds_read_b128 v[130:133], v219 offset:18432
	ds_read_b128 v[134:137], v220 offset:18432
	ds_read_b128 v[138:141], v219 offset:23040
	s_waitcnt lgkmcnt(11)
	v_mfma_f32_32x32x16_bf16 v[18:33], v[154:157], v[158:161], v[18:33]
	ds_read_b128 v[142:145], v219 offset:18464
	ds_read_b128 v[146:149], v220 offset:18464
	ds_read_b128 v[150:153], v219 offset:23072
	s_waitcnt lgkmcnt(13)
	v_mfma_f32_32x32x16_bf16 v[2:17], v[162:165], v[158:161], v[2:17]
	s_waitcnt lgkmcnt(11)
	v_mfma_f32_32x32x16_bf16 v[18:33], v[166:169], v[170:173], v[18:33]
	s_waitcnt lgkmcnt(10)
	v_mfma_f32_32x32x16_bf16 v[2:17], v[174:177], v[170:173], v[2:17]
	s_waitcnt lgkmcnt(0)
	s_barrier
	ds_read_b128 v[154:157], v219 offset:18496
	ds_read_b128 v[158:161], v220 offset:18496
	ds_read_b128 v[162:165], v219 offset:23104
	v_mfma_f32_32x32x16_bf16 v[18:33], v[130:133], v[134:137], v[18:33]
	ds_read_b128 v[166:169], v219 offset:18528
	ds_read_b128 v[170:173], v220 offset:18528
	ds_read_b128 v[174:177], v219 offset:23136
	v_mfma_f32_32x32x16_bf16 v[2:17], v[138:141], v[134:137], v[2:17]
	s_waitcnt vmcnt(16)
	ds_write_b128 v218, v[66:69]
	ds_write_b128 v218, v[70:73] offset:9216
	v_mfma_f32_32x32x16_bf16 v[18:33], v[142:145], v[146:149], v[18:33]
	ds_write_b128 v223, v[74:77]
	ds_write_b128 v223, v[78:81] offset:9216
	v_mfma_f32_32x32x16_bf16 v[2:17], v[150:153], v[146:149], v[2:17]
	global_load_dwordx4 v[66:69], v212, s[0:1] offset:256
	global_load_dwordx4 v[70:73], v212, s[2:3] offset:256
	global_load_dwordx4 v[74:77], v216, s[4:5] offset:256
	global_load_dwordx4 v[78:81], v216, s[6:7] offset:256
	ds_read_b128 v[130:133], v219 offset:36864
	ds_read_b128 v[134:137], v220 offset:36864
	ds_read_b128 v[138:141], v219 offset:41472
	s_waitcnt lgkmcnt(11)
	v_mfma_f32_32x32x16_bf16 v[18:33], v[154:157], v[158:161], v[18:33]
	ds_read_b128 v[142:145], v219 offset:36896
	ds_read_b128 v[146:149], v220 offset:36896
	ds_read_b128 v[150:153], v219 offset:41504
	s_waitcnt lgkmcnt(13)
	v_mfma_f32_32x32x16_bf16 v[2:17], v[162:165], v[158:161], v[2:17]
	s_waitcnt lgkmcnt(11)
	v_mfma_f32_32x32x16_bf16 v[18:33], v[166:169], v[170:173], v[18:33]
	s_waitcnt lgkmcnt(10)
	v_mfma_f32_32x32x16_bf16 v[2:17], v[174:177], v[170:173], v[2:17]
	s_waitcnt lgkmcnt(0)
	s_barrier
; DI float bflo(unsigned w) { return __uint_as_float(w << 16); }
; DI float bfhi(unsigned w) { return __uint_as_float(w & 0xffff0000u); }
; template <class ACC>
; DI void merge_branch(const Prm& p, u16* smem, const u16* W, const u16* X, int ld, int bi, int n0, int m0, ACC& macc) {
;     ...
;   auto epi = [&](f32x16 (&acc)[2], int wm, int wn, int lane) __attribute__((always_inline)) {
;     const int lr = lane & 31, lh = lane >> 5;
;     const int tok = m0 + wn * 32 + lr;
; #pragma unroll
;     for (int i = 0; i < 2; ++i)
; #pragma unroll
;       for (int h2 = 0; h2 < 2; ++h2) {
;         const int n = n0 + wm * 64 + i * 32 + 16 * lh + 8 * h2;
;         const u32x4 gz = *(const u32x4*)(p.zg + (size_t)tok * 4096 + bi * 1024 + n);
; #pragma unroll
;         for (int e = 0; e < 4; ++e) {
;           macc[i][8 * h2 + 2 * e] += bflo(gz[e]) * acc[i][8 * h2 + 2 * e];
;           macc[i][8 * h2 + 2 * e + 1] += bfhi(gz[e]) * acc[i][8 * h2 + 2 * e + 1];
;         }
; DI void phase_merge(const Prm& p, u16* smem, int l, int& base) {
;     ...
;     merge_branch(p, smem, p.PaT + (size_t)l * 1024 * 768, p.UT, 768, 0, n0, m0, macc);
;     merge_branch(p, smem, p.PbT + (size_t)l * 1024 * 128, p.ob, 128, 1, n0, m0, macc);
	ds_read_b128 v[154:157], v219 offset:36928
	ds_read_b128 v[158:161], v220 offset:36928
	ds_read_b128 v[162:165], v219 offset:41536
	v_mfma_f32_32x32x16_bf16 v[18:33], v[130:133], v[134:137], v[18:33]
	ds_read_b128 v[166:169], v219 offset:36960
	ds_read_b128 v[170:173], v220 offset:36960
	ds_read_b128 v[174:177], v219 offset:41568
	v_mfma_f32_32x32x16_bf16 v[2:17], v[138:141], v[134:137], v[2:17]
	s_waitcnt vmcnt(16)
	ds_write_b128 v218, v[82:85] offset:18432
	ds_write_b128 v218, v[86:89] offset:27648
	v_mfma_f32_32x32x16_bf16 v[18:33], v[142:145], v[146:149], v[18:33]
	ds_write_b128 v223, v[90:93] offset:18432
	ds_write_b128 v223, v[94:97] offset:27648
	v_mfma_f32_32x32x16_bf16 v[2:17], v[150:153], v[146:149], v[2:17]
	global_load_dwordx4 v[82:85], v212, s[0:1] offset:384
	global_load_dwordx4 v[86:89], v212, s[2:3] offset:384
	global_load_dwordx4 v[90:93], v216, s[4:5] offset:384
	global_load_dwordx4 v[94:97], v216, s[6:7] offset:384
	ds_read_b128 v[130:133], v219
	ds_read_b128 v[134:137], v220
	ds_read_b128 v[138:141], v219 offset:4608
	s_waitcnt lgkmcnt(11)
	v_mfma_f32_32x32x16_bf16 v[18:33], v[154:157], v[158:161], v[18:33]
	ds_read_b128 v[142:145], v219 offset:32
	ds_read_b128 v[146:149], v220 offset:32
	ds_read_b128 v[150:153], v219 offset:4640
	s_waitcnt lgkmcnt(13)
	v_mfma_f32_32x32x16_bf16 v[2:17], v[162:165], v[158:161], v[2:17]
	s_waitcnt lgkmcnt(11)
	v_mfma_f32_32x32x16_bf16 v[18:33], v[166:169], v[170:173], v[18:33]
	s_waitcnt lgkmcnt(10)
	v_mfma_f32_32x32x16_bf16 v[2:17], v[174:177], v[170:173], v[2:17]
	s_waitcnt vmcnt(28)
	s_nop 15
	v_lshlrev_b32_e32 v226, 16, v178
	v_and_b32_e32 v227, 0xffff0000, v178
	v_pk_mul_f32 v[34:35], v[226:227], v[18:19]
	v_lshlrev_b32_e32 v228, 16, v179
	v_and_b32_e32 v229, 0xffff0000, v179
	v_pk_mul_f32 v[36:37], v[228:229], v[20:21]
	v_lshlrev_b32_e32 v234, 16, v180
	v_and_b32_e32 v235, 0xffff0000, v180
	v_pk_mul_f32 v[38:39], v[234:235], v[22:23]
	v_lshlrev_b32_e32 v236, 16, v181
	v_and_b32_e32 v237, 0xffff0000, v181
	v_pk_mul_f32 v[40:41], v[236:237], v[24:25]
	v_lshlrev_b32_e32 v226, 16, v182
	v_and_b32_e32 v227, 0xffff0000, v182
	v_pk_mul_f32 v[42:43], v[226:227], v[26:27]
	v_lshlrev_b32_e32 v228, 16, v183
	v_and_b32_e32 v229, 0xffff0000, v183
	v_pk_mul_f32 v[44:45], v[228:229], v[28:29]
	v_lshlrev_b32_e32 v234, 16, v184
	v_and_b32_e32 v235, 0xffff0000, v184
	v_pk_mul_f32 v[46:47], v[234:235], v[30:31]
	v_lshlrev_b32_e32 v236, 16, v185
	v_and_b32_e32 v237, 0xffff0000, v185
	v_pk_mul_f32 v[48:49], v[236:237], v[32:33]
	v_lshlrev_b32_e32 v226, 16, v186
	v_and_b32_e32 v227, 0xffff0000, v186
	v_pk_mul_f32 v[50:51], v[226:227], v[2:3]
	v_lshlrev_b32_e32 v228, 16, v187
	v_and_b32_e32 v229, 0xffff0000, v187
	v_pk_mul_f32 v[52:53], v[228:229], v[4:5]
	v_lshlrev_b32_e32 v234, 16, v188
	v_and_b32_e32 v235, 0xffff0000, v188
	v_pk_mul_f32 v[54:55], v[234:235], v[6:7]
	v_lshlrev_b32_e32 v236, 16, v189
	v_and_b32_e32 v237, 0xffff0000, v189
	v_pk_mul_f32 v[56:57], v[236:237], v[8:9]
	v_lshlrev_b32_e32 v226, 16, v190
	v_and_b32_e32 v227, 0xffff0000, v190
	v_pk_mul_f32 v[58:59], v[226:227], v[10:11]
	v_lshlrev_b32_e32 v228, 16, v191
	v_and_b32_e32 v229, 0xffff0000, v191
	v_pk_mul_f32 v[60:61], v[228:229], v[12:13]
	v_lshlrev_b32_e32 v234, 16, v192
	v_and_b32_e32 v235, 0xffff0000, v192
	v_pk_mul_f32 v[62:63], v[234:235], v[14:15]
	v_lshlrev_b32_e32 v236, 16, v193
	v_and_b32_e32 v237, 0xffff0000, v193
	v_pk_mul_f32 v[64:65], v[236:237], v[16:17]
	s_waitcnt lgkmcnt(0)
	s_barrier
	ds_read_b128 v[154:157], v219 offset:64
	ds_read_b128 v[158:161], v220 offset:64
	ds_read_b128 v[162:165], v219 offset:4672
	v_mfma_f32_32x32x16_bf16 v[18:33], v[130:133], v[134:137], 0
	ds_read_b128 v[166:169], v219 offset:96
	ds_read_b128 v[170:173], v220 offset:96
	ds_read_b128 v[174:177], v219 offset:4704
	v_mfma_f32_32x32x16_bf16 v[2:17], v[138:141], v[134:137], 0
	s_waitcnt vmcnt(12)
	ds_write_b128 v218, v[98:101] offset:36864
	ds_write_b128 v218, v[102:105] offset:46080
	v_mfma_f32_32x32x16_bf16 v[18:33], v[142:145], v[146:149], v[18:33]
	ds_write_b128 v223, v[106:109] offset:36864
	ds_write_b128 v223, v[110:113] offset:46080
	v_mfma_f32_32x32x16_bf16 v[2:17], v[150:153], v[146:149], v[2:17]
	global_load_dwordx4 v[98:101], v212, s[0:1] offset:512
	global_load_dwordx4 v[102:105], v212, s[2:3] offset:512
	global_load_dwordx4 v[106:109], v216, s[4:5] offset:512
	global_load_dwordx4 v[110:113], v216, s[6:7] offset:512
	global_load_dwordx4 v[178:181], v221, s[10:11]
	global_load_dwordx4 v[182:185], v221, s[10:11] offset:16
	global_load_dwordx4 v[186:189], v221, s[10:11] offset:64
	global_load_dwordx4 v[190:193], v221, s[10:11] offset:80
	ds_read_b128 v[130:133], v219 offset:18432
	ds_read_b128 v[134:137], v220 offset:18432
	ds_read_b128 v[138:141], v219 offset:23040
	s_waitcnt lgkmcnt(11)
	v_mfma_f32_32x32x16_bf16 v[18:33], v[154:157], v[158:161], v[18:33]
	ds_read_b128 v[142:145], v219 offset:18464
	ds_read_b128 v[146:149], v220 offset:18464
	ds_read_b128 v[150:153], v219 offset:23072
	s_waitcnt lgkmcnt(13)
	v_mfma_f32_32x32x16_bf16 v[2:17], v[162:165], v[158:161], v[2:17]
	s_waitcnt lgkmcnt(11)
	v_mfma_f32_32x32x16_bf16 v[18:33], v[166:169], v[170:173], v[18:33]
	s_waitcnt lgkmcnt(10)
	v_mfma_f32_32x32x16_bf16 v[2:17], v[174:177], v[170:173], v[2:17]
	s_waitcnt lgkmcnt(0)
	s_barrier
; DI float bflo(unsigned w) { return __uint_as_float(w << 16); }
; DI float bfhi(unsigned w) { return __uint_as_float(w & 0xffff0000u); }
; template <class ACC>
; DI void merge_branch(const Prm& p, u16* smem, const u16* W, const u16* X, int ld, int bi, int n0, int m0, ACC& macc) {
;     ...
;   auto epi = [&](f32x16 (&acc)[2], int wm, int wn, int lane) __attribute__((always_inline)) {
;     const int lr = lane & 31, lh = lane >> 5;
;     const int tok = m0 + wn * 32 + lr;
; #pragma unroll
;     for (int i = 0; i < 2; ++i)
; #pragma unroll
;       for (int h2 = 0; h2 < 2; ++h2) {
;         const int n = n0 + wm * 64 + i * 32 + 16 * lh + 8 * h2;
;         const u32x4 gz = *(const u32x4*)(p.zg + (size_t)tok * 4096 + bi * 1024 + n);
; #pragma unroll
;         for (int e = 0; e < 4; ++e) {
;           macc[i][8 * h2 + 2 * e] += bflo(gz[e]) * acc[i][8 * h2 + 2 * e];
;           macc[i][8 * h2 + 2 * e + 1] += bfhi(gz[e]) * acc[i][8 * h2 + 2 * e + 1];
;         }
; DI void phase_merge(const Prm& p, u16* smem, int l, int& base) {
;     ...
;     merge_branch(p, smem, p.PbT + (size_t)l * 1024 * 128, p.ob, 128, 1, n0, m0, macc);
;     ...
;     merge_branch(p, smem, p.PdT + (size_t)l * 1024 * 256, p.od, 256, 3, n0, m0, macc);
	ds_read_b128 v[154:157], v219 offset:18496
	ds_read_b128 v[158:161], v220 offset:18496
	ds_read_b128 v[162:165], v219 offset:23104
	v_mfma_f32_32x32x16_bf16 v[18:33], v[130:133], v[134:137], v[18:33]
	ds_read_b128 v[166:169], v219 offset:18528
	ds_read_b128 v[170:173], v220 offset:18528
	ds_read_b128 v[174:177], v219 offset:23136
	v_mfma_f32_32x32x16_bf16 v[2:17], v[138:141], v[134:137], v[2:17]
	s_waitcnt vmcnt(16)
	ds_write_b128 v218, v[114:117]
	ds_write_b128 v218, v[118:121] offset:9216
	v_mfma_f32_32x32x16_bf16 v[18:33], v[142:145], v[146:149], v[18:33]
	ds_write_b128 v223, v[122:125]
	ds_write_b128 v223, v[126:129] offset:9216
	v_mfma_f32_32x32x16_bf16 v[2:17], v[150:153], v[146:149], v[2:17]
	global_load_dwordx4 v[114:117], v212, s[0:1] offset:640
	global_load_dwordx4 v[118:121], v212, s[2:3] offset:640
	global_load_dwordx4 v[122:125], v216, s[4:5] offset:640
	global_load_dwordx4 v[126:129], v216, s[6:7] offset:640
	ds_read_b128 v[130:133], v219 offset:36864
	ds_read_b128 v[134:137], v220 offset:36864
	ds_read_b128 v[138:141], v219 offset:41472
	s_waitcnt lgkmcnt(11)
	v_mfma_f32_32x32x16_bf16 v[18:33], v[154:157], v[158:161], v[18:33]
	ds_read_b128 v[142:145], v219 offset:36896
	ds_read_b128 v[146:149], v220 offset:36896
	ds_read_b128 v[150:153], v219 offset:41504
	s_waitcnt lgkmcnt(13)
	v_mfma_f32_32x32x16_bf16 v[2:17], v[162:165], v[158:161], v[2:17]
	s_waitcnt lgkmcnt(11)
	v_mfma_f32_32x32x16_bf16 v[18:33], v[166:169], v[170:173], v[18:33]
	s_waitcnt lgkmcnt(10)
	v_mfma_f32_32x32x16_bf16 v[2:17], v[174:177], v[170:173], v[2:17]
	s_waitcnt vmcnt(28)
	s_nop 15
	v_lshlrev_b32_e32 v226, 16, v194
	v_and_b32_e32 v227, 0xffff0000, v194
	v_pk_fma_f32 v[34:35], v[226:227], v[18:19], v[34:35]
	v_lshlrev_b32_e32 v228, 16, v195
	v_and_b32_e32 v229, 0xffff0000, v195
	v_pk_fma_f32 v[36:37], v[228:229], v[20:21], v[36:37]
	v_lshlrev_b32_e32 v234, 16, v196
	v_and_b32_e32 v235, 0xffff0000, v196
	v_pk_fma_f32 v[38:39], v[234:235], v[22:23], v[38:39]
	v_lshlrev_b32_e32 v236, 16, v197
	v_and_b32_e32 v237, 0xffff0000, v197
	v_pk_fma_f32 v[40:41], v[236:237], v[24:25], v[40:41]
	v_lshlrev_b32_e32 v226, 16, v198
	v_and_b32_e32 v227, 0xffff0000, v198
	v_pk_fma_f32 v[42:43], v[226:227], v[26:27], v[42:43]
	v_lshlrev_b32_e32 v228, 16, v199
	v_and_b32_e32 v229, 0xffff0000, v199
	v_pk_fma_f32 v[44:45], v[228:229], v[28:29], v[44:45]
	v_lshlrev_b32_e32 v234, 16, v200
	v_and_b32_e32 v235, 0xffff0000, v200
	v_pk_fma_f32 v[46:47], v[234:235], v[30:31], v[46:47]
	v_lshlrev_b32_e32 v236, 16, v201
	v_and_b32_e32 v237, 0xffff0000, v201
	v_pk_fma_f32 v[48:49], v[236:237], v[32:33], v[48:49]
	v_lshlrev_b32_e32 v226, 16, v202
	v_and_b32_e32 v227, 0xffff0000, v202
	v_pk_fma_f32 v[50:51], v[226:227], v[2:3], v[50:51]
	v_lshlrev_b32_e32 v228, 16, v203
	v_and_b32_e32 v229, 0xffff0000, v203
	v_pk_fma_f32 v[52:53], v[228:229], v[4:5], v[52:53]
	v_lshlrev_b32_e32 v234, 16, v204
	v_and_b32_e32 v235, 0xffff0000, v204
	v_pk_fma_f32 v[54:55], v[234:235], v[6:7], v[54:55]
	v_lshlrev_b32_e32 v236, 16, v205
	v_and_b32_e32 v237, 0xffff0000, v205
	v_pk_fma_f32 v[56:57], v[236:237], v[8:9], v[56:57]
	v_lshlrev_b32_e32 v226, 16, v206
	v_and_b32_e32 v227, 0xffff0000, v206
	v_pk_fma_f32 v[58:59], v[226:227], v[10:11], v[58:59]
	v_lshlrev_b32_e32 v228, 16, v207
	v_and_b32_e32 v229, 0xffff0000, v207
	v_pk_fma_f32 v[60:61], v[228:229], v[12:13], v[60:61]
	v_lshlrev_b32_e32 v234, 16, v208
	v_and_b32_e32 v235, 0xffff0000, v208
	v_pk_fma_f32 v[62:63], v[234:235], v[14:15], v[62:63]
	v_lshlrev_b32_e32 v236, 16, v209
	v_and_b32_e32 v237, 0xffff0000, v209
	v_pk_fma_f32 v[64:65], v[236:237], v[16:17], v[64:65]
	s_waitcnt lgkmcnt(0)
	s_barrier
	ds_read_b128 v[154:157], v219 offset:36928
	ds_read_b128 v[158:161], v220 offset:36928
	ds_read_b128 v[162:165], v219 offset:41536
	v_mfma_f32_32x32x16_bf16 v[18:33], v[130:133], v[134:137], 0
	ds_read_b128 v[166:169], v219 offset:36960
	ds_read_b128 v[170:173], v220 offset:36960
	ds_read_b128 v[174:177], v219 offset:41568
	v_mfma_f32_32x32x16_bf16 v[2:17], v[138:141], v[134:137], 0
	s_waitcnt vmcnt(16)
	ds_write_b128 v218, v[66:69] offset:18432
	ds_write_b128 v218, v[70:73] offset:27648
	v_mfma_f32_32x32x16_bf16 v[18:33], v[142:145], v[146:149], v[18:33]
	ds_write_b128 v223, v[74:77] offset:18432
	ds_write_b128 v223, v[78:81] offset:27648
	v_mfma_f32_32x32x16_bf16 v[2:17], v[150:153], v[146:149], v[2:17]
	s_mul_i32 s52, s58, 0x200
	s_add_u32 s0, s44, s52
	s_addc_u32 s1, s45, 0
	s_add_u32 s2, s0, 0x8000
	s_addc_u32 s3, s1, 0
	s_mul_i32 s52, s59, 0x200
	s_add_u32 s4, s40, s52
	s_addc_u32 s5, s41, 0
	s_add_u32 s6, s4, 0x8000
	s_addc_u32 s7, s5, 0
	global_load_dwordx4 v[66:69], v213, s[0:1]
	global_load_dwordx4 v[70:73], v213, s[2:3]
	global_load_dwordx4 v[74:77], v217, s[4:5]
	global_load_dwordx4 v[78:81], v217, s[6:7]
	global_load_dwordx4 v[194:197], v221, s[10:11] offset:2048
	global_load_dwordx4 v[198:201], v221, s[10:11] offset:2064
	global_load_dwordx4 v[202:205], v221, s[10:11] offset:2112
	global_load_dwordx4 v[206:209], v221, s[10:11] offset:2128
	ds_read_b128 v[130:133], v219
	ds_read_b128 v[134:137], v220
	ds_read_b128 v[138:141], v219 offset:4608
	s_waitcnt lgkmcnt(11)
	v_mfma_f32_32x32x16_bf16 v[18:33], v[154:157], v[158:161], v[18:33]
	ds_read_b128 v[142:145], v219 offset:32
	ds_read_b128 v[146:149], v220 offset:32
	ds_read_b128 v[150:153], v219 offset:4640
	s_waitcnt lgkmcnt(13)
	v_mfma_f32_32x32x16_bf16 v[2:17], v[162:165], v[158:161], v[2:17]
	s_waitcnt lgkmcnt(11)
	v_mfma_f32_32x32x16_bf16 v[18:33], v[166:169], v[170:173], v[18:33]
	s_waitcnt lgkmcnt(10)
	v_mfma_f32_32x32x16_bf16 v[2:17], v[174:177], v[170:173], v[2:17]
	s_waitcnt lgkmcnt(0)
	s_barrier
; DI f32x16 mfma(bf16x8 a, bf16x8 b, f32x16 c) { return __builtin_amdgcn_mfma_f32_32x32x16_bf16(a, b, c, 0, 0, 0); }
; template <bool RFA, bool RFB, class LA, class LB, class EPI>
; DI void gemm_tile2s(u16* smem, int nk, LA la, LB lb, EPI epi) {
;     ...
;   auto compute = [&](int buf) __attribute__((always_inline)) {
;     const u16* Ab = As + buf * TILE_ELEMS + (wm * 64 + lr) * LDT + lh * 8;
;     const u16* Bb = Bs + buf * TILE_ELEMS + (wn * 32 + lr) * LDT + lh * 8;
; #pragma unroll
;     for (int ks = 0; ks < 4; ++ks) {
;       const bf16x8 a0 = *(const bf16x8*)(Ab + ks * 16);
;       const bf16x8 a1 = *(const bf16x8*)(Ab + 32 * LDT + ks * 16);
;       const bf16x8 b = *(const bf16x8*)(Bb + ks * 16);
;       acc[0] = mfma(a0, b, acc[0]);
;       acc[1] = mfma(a1, b, acc[1]);
;     }
;   };
;     ...
;     if (kt + 1 < nk) { stl(ra1, rb1, 1); if (kt + 3 < nk) ld(ra1, rb1, kt + 3); }
;     __syncthreads();
;     if (kt + 1 < nk) {
;       compute(1);
;       if (kt + 2 < nk) { stl(ra0, rb0, 0); if (kt + 4 < nk) ld(ra0, rb0, kt + 4); }
;       __syncthreads();
; DI void phase_merge(const Prm& p, u16* smem, int l, int& base) {
;     ...
;     merge_branch(p, smem, p.PdT + (size_t)l * 1024 * 256, p.od, 256, 3, n0, m0, macc);
	ds_read_b128 v[154:157], v219 offset:64
	ds_read_b128 v[158:161], v220 offset:64
	ds_read_b128 v[162:165], v219 offset:4672
	v_mfma_f32_32x32x16_bf16 v[18:33], v[130:133], v[134:137], v[18:33]
	ds_read_b128 v[166:169], v219 offset:96
	ds_read_b128 v[170:173], v220 offset:96
	ds_read_b128 v[174:177], v219 offset:4704
	v_mfma_f32_32x32x16_bf16 v[2:17], v[138:141], v[134:137], v[2:17]
	s_waitcnt vmcnt(20)
	ds_write_b128 v218, v[82:85] offset:36864
	ds_write_b128 v218, v[86:89] offset:46080
	v_mfma_f32_32x32x16_bf16 v[18:33], v[142:145], v[146:149], v[18:33]
	ds_write_b128 v223, v[90:93] offset:36864
	ds_write_b128 v223, v[94:97] offset:46080
	v_mfma_f32_32x32x16_bf16 v[2:17], v[150:153], v[146:149], v[2:17]
	global_load_dwordx4 v[82:85], v213, s[0:1] offset:128
	global_load_dwordx4 v[86:89], v213, s[2:3] offset:128
	global_load_dwordx4 v[90:93], v217, s[4:5] offset:128
	global_load_dwordx4 v[94:97], v217, s[6:7] offset:128
	ds_read_b128 v[130:133], v219 offset:18432
	ds_read_b128 v[134:137], v220 offset:18432
	ds_read_b128 v[138:141], v219 offset:23040
	s_waitcnt lgkmcnt(11)
	v_mfma_f32_32x32x16_bf16 v[18:33], v[154:157], v[158:161], v[18:33]
	ds_read_b128 v[142:145], v219 offset:18464
	ds_read_b128 v[146:149], v220 offset:18464
	ds_read_b128 v[150:153], v219 offset:23072
	s_waitcnt lgkmcnt(13)
	v_mfma_f32_32x32x16_bf16 v[2:17], v[162:165], v[158:161], v[2:17]
	s_waitcnt lgkmcnt(11)
	v_mfma_f32_32x32x16_bf16 v[18:33], v[166:169], v[170:173], v[18:33]
	s_waitcnt lgkmcnt(10)
	v_mfma_f32_32x32x16_bf16 v[2:17], v[174:177], v[170:173], v[2:17]
	s_waitcnt lgkmcnt(0)
	s_barrier
	ds_read_b128 v[154:157], v219 offset:18496
	ds_read_b128 v[158:161], v220 offset:18496
	ds_read_b128 v[162:165], v219 offset:23104
	v_mfma_f32_32x32x16_bf16 v[18:33], v[130:133], v[134:137], v[18:33]
	ds_read_b128 v[166:169], v219 offset:18528
	ds_read_b128 v[170:173], v220 offset:18528
	ds_read_b128 v[174:177], v219 offset:23136
	v_mfma_f32_32x32x16_bf16 v[2:17], v[138:141], v[134:137], v[2:17]
	s_waitcnt vmcnt(20)
	ds_write_b128 v218, v[98:101]
	ds_write_b128 v218, v[102:105] offset:9216
	v_mfma_f32_32x32x16_bf16 v[18:33], v[142:145], v[146:149], v[18:33]
	ds_write_b128 v223, v[106:109]
	ds_write_b128 v223, v[110:113] offset:9216
	v_mfma_f32_32x32x16_bf16 v[2:17], v[150:153], v[146:149], v[2:17]
	global_load_dwordx4 v[98:101], v213, s[0:1] offset:256
	global_load_dwordx4 v[102:105], v213, s[2:3] offset:256
	global_load_dwordx4 v[106:109], v217, s[4:5] offset:256
	global_load_dwordx4 v[110:113], v217, s[6:7] offset:256
	ds_read_b128 v[130:133], v219 offset:36864
	ds_read_b128 v[134:137], v220 offset:36864
	ds_read_b128 v[138:141], v219 offset:41472
	s_waitcnt lgkmcnt(11)
	v_mfma_f32_32x32x16_bf16 v[18:33], v[154:157], v[158:161], v[18:33]
	ds_read_b128 v[142:145], v219 offset:36896
	ds_read_b128 v[146:149], v220 offset:36896
	ds_read_b128 v[150:153], v219 offset:41504
	s_waitcnt lgkmcnt(13)
	v_mfma_f32_32x32x16_bf16 v[2:17], v[162:165], v[158:161], v[2:17]
	s_waitcnt lgkmcnt(11)
	v_mfma_f32_32x32x16_bf16 v[18:33], v[166:169], v[170:173], v[18:33]
	s_waitcnt lgkmcnt(10)
	v_mfma_f32_32x32x16_bf16 v[2:17], v[174:177], v[170:173], v[2:17]
	s_waitcnt lgkmcnt(0)
	s_barrier
	ds_read_b128 v[154:157], v219 offset:36928
	ds_read_b128 v[158:161], v220 offset:36928
	ds_read_b128 v[162:165], v219 offset:41536
	v_mfma_f32_32x32x16_bf16 v[18:33], v[130:133], v[134:137], v[18:33]
	ds_read_b128 v[166:169], v219 offset:36960
	ds_read_b128 v[170:173], v220 offset:36960
	ds_read_b128 v[174:177], v219 offset:41568
	v_mfma_f32_32x32x16_bf16 v[2:17], v[138:141], v[134:137], v[2:17]
	s_waitcnt vmcnt(16)
	ds_write_b128 v218, v[114:117] offset:18432
	ds_write_b128 v218, v[118:121] offset:27648
	v_mfma_f32_32x32x16_bf16 v[18:33], v[142:145], v[146:149], v[18:33]
	ds_write_b128 v223, v[122:125] offset:18432
	ds_write_b128 v223, v[126:129] offset:27648
	v_mfma_f32_32x32x16_bf16 v[2:17], v[150:153], v[146:149], v[2:17]
	global_load_dwordx4 v[114:117], v213, s[0:1] offset:384
	global_load_dwordx4 v[118:121], v213, s[2:3] offset:384
	global_load_dwordx4 v[122:125], v217, s[4:5] offset:384
	global_load_dwordx4 v[126:129], v217, s[6:7] offset:384
	ds_read_b128 v[130:133], v219
	ds_read_b128 v[134:137], v220
	ds_read_b128 v[138:141], v219 offset:4608
	s_waitcnt lgkmcnt(11)
	v_mfma_f32_32x32x16_bf16 v[18:33], v[154:157], v[158:161], v[18:33]
	ds_read_b128 v[142:145], v219 offset:32
	ds_read_b128 v[146:149], v220 offset:32
	ds_read_b128 v[150:153], v219 offset:4640
	s_waitcnt lgkmcnt(13)
	v_mfma_f32_32x32x16_bf16 v[2:17], v[162:165], v[158:161], v[2:17]
	s_waitcnt lgkmcnt(11)
	v_mfma_f32_32x32x16_bf16 v[18:33], v[166:169], v[170:173], v[18:33]
	s_waitcnt lgkmcnt(10)
	v_mfma_f32_32x32x16_bf16 v[2:17], v[174:177], v[170:173], v[2:17]
	s_waitcnt lgkmcnt(0)
	s_barrier
; DI float bflo(unsigned w) { return __uint_as_float(w << 16); }
; DI float bfhi(unsigned w) { return __uint_as_float(w & 0xffff0000u); }
; DI f32x16 zero16() { f32x16 z; for (int i = 0; i < 16; ++i) z[i] = 0.f; return z; }
; #define TASK_LOOP(t, nt, base) for (int t = (int)((blockIdx.x + gridDim.x - ((unsigned)(base) % gridDim.x)) % gridDim.x); t < (nt); t += gridDim.x)
; template <class ACC>
; DI void merge_branch(const Prm& p, u16* smem, const u16* W, const u16* X, int ld, int bi, int n0, int m0, ACC& macc) {
;     ...
;   auto epi = [&](f32x16 (&acc)[2], int wm, int wn, int lane) __attribute__((always_inline)) {
;     const int lr = lane & 31, lh = lane >> 5;
;     const int tok = m0 + wn * 32 + lr;
; #pragma unroll
;     for (int i = 0; i < 2; ++i)
; #pragma unroll
;       for (int h2 = 0; h2 < 2; ++h2) {
;         const int n = n0 + wm * 64 + i * 32 + 16 * lh + 8 * h2;
;         const u32x4 gz = *(const u32x4*)(p.zg + (size_t)tok * 4096 + bi * 1024 + n);
; #pragma unroll
;         for (int e = 0; e < 4; ++e) {
;           macc[i][8 * h2 + 2 * e] += bflo(gz[e]) * acc[i][8 * h2 + 2 * e];
;           macc[i][8 * h2 + 2 * e + 1] += bfhi(gz[e]) * acc[i][8 * h2 + 2 * e + 1];
;         }
; DI void phase_merge(const Prm& p, u16* smem, int l, int& base) {
;   TASK_LOOP(t, 8 * 128, base) {
;     const int tn = t & 7, tm = t >> 3, n0 = tn * 128, m0 = tm * 128;
;     f32x16 macc[2];
;     macc[0] = zero16(); macc[1] = zero16();
;     merge_branch(p, smem, p.PaT + (size_t)l * 1024 * 768, p.UT, 768, 0, n0, m0, macc);
;     merge_branch(p, smem, p.PbT + (size_t)l * 1024 * 128, p.ob, 128, 1, n0, m0, macc);
;     ...
;     merge_branch(p, smem, p.PdT + (size_t)l * 1024 * 256, p.od, 256, 3, n0, m0, macc);
	ds_read_b128 v[154:157], v219 offset:64
	ds_read_b128 v[158:161], v220 offset:64
	ds_read_b128 v[162:165], v219 offset:4672
	v_mfma_f32_32x32x16_bf16 v[18:33], v[130:133], v[134:137], v[18:33]
	ds_read_b128 v[166:169], v219 offset:96
	ds_read_b128 v[170:173], v220 offset:96
	ds_read_b128 v[174:177], v219 offset:4704
	v_mfma_f32_32x32x16_bf16 v[2:17], v[138:141], v[134:137], v[2:17]
	s_waitcnt vmcnt(16)
	ds_write_b128 v218, v[66:69] offset:36864
	ds_write_b128 v218, v[70:73] offset:46080
	v_mfma_f32_32x32x16_bf16 v[18:33], v[142:145], v[146:149], v[18:33]
	ds_write_b128 v223, v[74:77] offset:36864
	ds_write_b128 v223, v[78:81] offset:46080
	v_mfma_f32_32x32x16_bf16 v[2:17], v[150:153], v[146:149], v[2:17]
	s_add_i32 s50, s31, s30
	s_cmpk_lt_i32 s50, 0x400
	s_cselect_b32 s50, s50, s31
	s_and_b32 s60, s50, 7
	s_lshl_b32 s60, s60, 7
	s_lshr_b32 s61, s50, 3
	s_lshl_b32 s61, s61, 7
	s_mul_i32 s52, s60, 0x600
	s_add_u32 s0, s16, s52
	s_addc_u32 s1, s17, 0
	s_add_u32 s2, s0, 0x18000
	s_addc_u32 s3, s1, 0
	s_mul_i32 s52, s61, 0x600
	s_add_u32 s4, s14, s52
	s_addc_u32 s5, s15, 0
	s_add_u32 s6, s4, 0x18000
	s_addc_u32 s7, s5, 0
	global_load_dwordx4 v[66:69], v210, s[0:1]
	global_load_dwordx4 v[70:73], v210, s[2:3]
	global_load_dwordx4 v[74:77], v214, s[4:5]
	global_load_dwordx4 v[78:81], v214, s[6:7]
	ds_read_b128 v[130:133], v219 offset:18432
	ds_read_b128 v[134:137], v220 offset:18432
	ds_read_b128 v[138:141], v219 offset:23040
	s_waitcnt lgkmcnt(11)
	v_mfma_f32_32x32x16_bf16 v[18:33], v[154:157], v[158:161], v[18:33]
	ds_read_b128 v[142:145], v219 offset:18464
	ds_read_b128 v[146:149], v220 offset:18464
	ds_read_b128 v[150:153], v219 offset:23072
	s_waitcnt lgkmcnt(13)
	v_mfma_f32_32x32x16_bf16 v[2:17], v[162:165], v[158:161], v[2:17]
	s_waitcnt lgkmcnt(11)
	v_mfma_f32_32x32x16_bf16 v[18:33], v[166:169], v[170:173], v[18:33]
	s_waitcnt lgkmcnt(10)
	v_mfma_f32_32x32x16_bf16 v[2:17], v[174:177], v[170:173], v[2:17]
	s_waitcnt lgkmcnt(0)
	s_barrier
	ds_read_b128 v[154:157], v219 offset:18496
	ds_read_b128 v[158:161], v220 offset:18496
	ds_read_b128 v[162:165], v219 offset:23104
	v_mfma_f32_32x32x16_bf16 v[18:33], v[130:133], v[134:137], v[18:33]
	ds_read_b128 v[166:169], v219 offset:18528
	ds_read_b128 v[170:173], v220 offset:18528
	ds_read_b128 v[174:177], v219 offset:23136
	v_mfma_f32_32x32x16_bf16 v[2:17], v[138:141], v[134:137], v[2:17]
	s_waitcnt vmcnt(12)
	ds_write_b128 v218, v[82:85]
	ds_write_b128 v218, v[86:89] offset:9216
	v_mfma_f32_32x32x16_bf16 v[18:33], v[142:145], v[146:149], v[18:33]
	ds_write_b128 v223, v[90:93]
	ds_write_b128 v223, v[94:97] offset:9216
	v_mfma_f32_32x32x16_bf16 v[2:17], v[150:153], v[146:149], v[2:17]
	global_load_dwordx4 v[82:85], v210, s[0:1] offset:128
	global_load_dwordx4 v[86:89], v210, s[2:3] offset:128
	global_load_dwordx4 v[90:93], v214, s[4:5] offset:128
	global_load_dwordx4 v[94:97], v214, s[6:7] offset:128
	ds_read_b128 v[130:133], v219 offset:36864
	ds_read_b128 v[134:137], v220 offset:36864
	ds_read_b128 v[138:141], v219 offset:41472
	s_waitcnt lgkmcnt(11)
	v_mfma_f32_32x32x16_bf16 v[18:33], v[154:157], v[158:161], v[18:33]
	ds_read_b128 v[142:145], v219 offset:36896
	ds_read_b128 v[146:149], v220 offset:36896
	ds_read_b128 v[150:153], v219 offset:41504
	s_waitcnt lgkmcnt(13)
	v_mfma_f32_32x32x16_bf16 v[2:17], v[162:165], v[158:161], v[2:17]
	s_waitcnt lgkmcnt(11)
	v_mfma_f32_32x32x16_bf16 v[18:33], v[166:169], v[170:173], v[18:33]
	s_waitcnt lgkmcnt(10)
	v_mfma_f32_32x32x16_bf16 v[2:17], v[174:177], v[170:173], v[2:17]
	s_waitcnt vmcnt(32)
	s_nop 15
	v_lshlrev_b32_e32 v226, 16, v178
	v_and_b32_e32 v227, 0xffff0000, v178
	v_pk_fma_f32 v[34:35], v[226:227], v[18:19], v[34:35]
	v_lshlrev_b32_e32 v228, 16, v179
	v_and_b32_e32 v229, 0xffff0000, v179
	v_pk_fma_f32 v[36:37], v[228:229], v[20:21], v[36:37]
	v_lshlrev_b32_e32 v234, 16, v180
	v_and_b32_e32 v235, 0xffff0000, v180
	v_pk_fma_f32 v[38:39], v[234:235], v[22:23], v[38:39]
	v_lshlrev_b32_e32 v236, 16, v181
	v_and_b32_e32 v237, 0xffff0000, v181
	v_pk_fma_f32 v[40:41], v[236:237], v[24:25], v[40:41]
	v_lshlrev_b32_e32 v226, 16, v182
	v_and_b32_e32 v227, 0xffff0000, v182
	v_pk_fma_f32 v[42:43], v[226:227], v[26:27], v[42:43]
	v_lshlrev_b32_e32 v228, 16, v183
	v_and_b32_e32 v229, 0xffff0000, v183
	v_pk_fma_f32 v[44:45], v[228:229], v[28:29], v[44:45]
	v_lshlrev_b32_e32 v234, 16, v184
	v_and_b32_e32 v235, 0xffff0000, v184
	v_pk_fma_f32 v[46:47], v[234:235], v[30:31], v[46:47]
	v_lshlrev_b32_e32 v236, 16, v185
	v_and_b32_e32 v237, 0xffff0000, v185
	v_pk_fma_f32 v[48:49], v[236:237], v[32:33], v[48:49]
	v_lshlrev_b32_e32 v226, 16, v186
	v_and_b32_e32 v227, 0xffff0000, v186
	v_pk_fma_f32 v[50:51], v[226:227], v[2:3], v[50:51]
	v_lshlrev_b32_e32 v228, 16, v187
	v_and_b32_e32 v229, 0xffff0000, v187
	v_pk_fma_f32 v[52:53], v[228:229], v[4:5], v[52:53]
	v_lshlrev_b32_e32 v234, 16, v188
	v_and_b32_e32 v235, 0xffff0000, v188
	v_pk_fma_f32 v[54:55], v[234:235], v[6:7], v[54:55]
	v_lshlrev_b32_e32 v236, 16, v189
	v_and_b32_e32 v237, 0xffff0000, v189
	v_pk_fma_f32 v[56:57], v[236:237], v[8:9], v[56:57]
	v_lshlrev_b32_e32 v226, 16, v190
	v_and_b32_e32 v227, 0xffff0000, v190
	v_pk_fma_f32 v[58:59], v[226:227], v[10:11], v[58:59]
	v_lshlrev_b32_e32 v228, 16, v191
	v_and_b32_e32 v229, 0xffff0000, v191
	v_pk_fma_f32 v[60:61], v[228:229], v[12:13], v[60:61]
	v_lshlrev_b32_e32 v234, 16, v192
	v_and_b32_e32 v235, 0xffff0000, v192
	v_pk_fma_f32 v[62:63], v[234:235], v[14:15], v[62:63]
	v_lshlrev_b32_e32 v236, 16, v193
	v_and_b32_e32 v237, 0xffff0000, v193
	v_pk_fma_f32 v[64:65], v[236:237], v[16:17], v[64:65]
	s_waitcnt lgkmcnt(0)
	s_barrier
; DI f32x16 mfma(bf16x8 a, bf16x8 b, f32x16 c) { return __builtin_amdgcn_mfma_f32_32x32x16_bf16(a, b, c, 0, 0, 0); }
; template <bool RFA, bool RFB, class LA, class LB, class EPI>
; DI void gemm_tile2s(u16* smem, int nk, LA la, LB lb, EPI epi) {
;     ...
;   auto compute = [&](int buf) __attribute__((always_inline)) {
;     const u16* Ab = As + buf * TILE_ELEMS + (wm * 64 + lr) * LDT + lh * 8;
;     const u16* Bb = Bs + buf * TILE_ELEMS + (wn * 32 + lr) * LDT + lh * 8;
; #pragma unroll
;     for (int ks = 0; ks < 4; ++ks) {
;       const bf16x8 a0 = *(const bf16x8*)(Ab + ks * 16);
;       const bf16x8 a1 = *(const bf16x8*)(Ab + 32 * LDT + ks * 16);
;       const bf16x8 b = *(const bf16x8*)(Bb + ks * 16);
;       acc[0] = mfma(a0, b, acc[0]);
;       acc[1] = mfma(a1, b, acc[1]);
;     }
;   };
;     ...
;     if (kt + 1 < nk) { stl(ra1, rb1, 1); if (kt + 3 < nk) ld(ra1, rb1, kt + 3); }
;     __syncthreads();
;     if (kt + 1 < nk) {
;       compute(1);
;       if (kt + 2 < nk) { stl(ra0, rb0, 0); if (kt + 4 < nk) ld(ra0, rb0, kt + 4); }
;       __syncthreads();
; DI void phase_merge(const Prm& p, u16* smem, int l, int& base) {
;     ...
;     merge_branch(p, smem, p.PdT + (size_t)l * 1024 * 256, p.od, 256, 3, n0, m0, macc);
	ds_read_b128 v[154:157], v219 offset:36928
	ds_read_b128 v[158:161], v220 offset:36928
	ds_read_b128 v[162:165], v219 offset:41536
	v_mfma_f32_32x32x16_bf16 v[18:33], v[130:133], v[134:137], 0
	ds_read_b128 v[166:169], v219 offset:36960
	ds_read_b128 v[170:173], v220 offset:36960
	ds_read_b128 v[174:177], v219 offset:41568
	v_mfma_f32_32x32x16_bf16 v[2:17], v[138:141], v[134:137], 0
	s_waitcnt vmcnt(12)
	ds_write_b128 v218, v[98:101] offset:18432
	ds_write_b128 v218, v[102:105] offset:27648
	v_mfma_f32_32x32x16_bf16 v[18:33], v[142:145], v[146:149], v[18:33]
	ds_write_b128 v223, v[106:109] offset:18432
	ds_write_b128 v223, v[110:113] offset:27648
	v_mfma_f32_32x32x16_bf16 v[2:17], v[150:153], v[146:149], v[2:17]
	global_load_dwordx4 v[98:101], v210, s[0:1] offset:256
	global_load_dwordx4 v[102:105], v210, s[2:3] offset:256
	global_load_dwordx4 v[106:109], v214, s[4:5] offset:256
	global_load_dwordx4 v[110:113], v214, s[6:7] offset:256
	ds_read_b128 v[130:133], v219
	ds_read_b128 v[134:137], v220
	ds_read_b128 v[138:141], v219 offset:4608
	s_waitcnt lgkmcnt(11)
	v_mfma_f32_32x32x16_bf16 v[18:33], v[154:157], v[158:161], v[18:33]
	ds_read_b128 v[142:145], v219 offset:32
	ds_read_b128 v[146:149], v220 offset:32
	ds_read_b128 v[150:153], v219 offset:4640
	s_waitcnt lgkmcnt(13)
	v_mfma_f32_32x32x16_bf16 v[2:17], v[162:165], v[158:161], v[2:17]
	s_waitcnt lgkmcnt(11)
	v_mfma_f32_32x32x16_bf16 v[18:33], v[166:169], v[170:173], v[18:33]
	s_waitcnt lgkmcnt(10)
	v_mfma_f32_32x32x16_bf16 v[2:17], v[174:177], v[170:173], v[2:17]
	s_waitcnt lgkmcnt(0)
	s_barrier
	ds_read_b128 v[154:157], v219 offset:64
	ds_read_b128 v[158:161], v220 offset:64
	ds_read_b128 v[162:165], v219 offset:4672
	v_mfma_f32_32x32x16_bf16 v[18:33], v[130:133], v[134:137], v[18:33]
	ds_read_b128 v[166:169], v219 offset:96
	ds_read_b128 v[170:173], v220 offset:96
	ds_read_b128 v[174:177], v219 offset:4704
	v_mfma_f32_32x32x16_bf16 v[2:17], v[138:141], v[134:137], v[2:17]
	s_waitcnt vmcnt(12)
	ds_write_b128 v218, v[114:117] offset:36864
	ds_write_b128 v218, v[118:121] offset:46080
	v_mfma_f32_32x32x16_bf16 v[18:33], v[142:145], v[146:149], v[18:33]
	ds_write_b128 v223, v[122:125] offset:36864
	ds_write_b128 v223, v[126:129] offset:46080
	v_mfma_f32_32x32x16_bf16 v[2:17], v[150:153], v[146:149], v[2:17]
	global_load_dwordx4 v[114:117], v210, s[0:1] offset:384
	global_load_dwordx4 v[118:121], v210, s[2:3] offset:384
	global_load_dwordx4 v[122:125], v214, s[4:5] offset:384
	global_load_dwordx4 v[126:129], v214, s[6:7] offset:384
	ds_read_b128 v[130:133], v219 offset:18432
	ds_read_b128 v[134:137], v220 offset:18432
	ds_read_b128 v[138:141], v219 offset:23040
	s_waitcnt lgkmcnt(11)
	v_mfma_f32_32x32x16_bf16 v[18:33], v[154:157], v[158:161], v[18:33]
	ds_read_b128 v[142:145], v219 offset:18464
	ds_read_b128 v[146:149], v220 offset:18464
	ds_read_b128 v[150:153], v219 offset:23072
	s_waitcnt lgkmcnt(13)
	v_mfma_f32_32x32x16_bf16 v[2:17], v[162:165], v[158:161], v[2:17]
	s_waitcnt lgkmcnt(11)
	v_mfma_f32_32x32x16_bf16 v[18:33], v[166:169], v[170:173], v[18:33]
	s_waitcnt lgkmcnt(10)
	v_mfma_f32_32x32x16_bf16 v[2:17], v[174:177], v[170:173], v[2:17]
	s_waitcnt lgkmcnt(0)
	s_barrier
	ds_read_b128 v[154:157], v219 offset:18496
	ds_read_b128 v[158:161], v220 offset:18496
	ds_read_b128 v[162:165], v219 offset:23104
	v_mfma_f32_32x32x16_bf16 v[18:33], v[130:133], v[134:137], v[18:33]
	ds_read_b128 v[166:169], v219 offset:18528
	ds_read_b128 v[170:173], v220 offset:18528
	ds_read_b128 v[174:177], v219 offset:23136
	v_mfma_f32_32x32x16_bf16 v[2:17], v[138:141], v[134:137], v[2:17]
	s_waitcnt vmcnt(12)
	ds_write_b128 v218, v[66:69]
	ds_write_b128 v218, v[70:73] offset:9216
	v_mfma_f32_32x32x16_bf16 v[18:33], v[142:145], v[146:149], v[18:33]
	ds_write_b128 v223, v[74:77]
	ds_write_b128 v223, v[78:81] offset:9216
	v_mfma_f32_32x32x16_bf16 v[2:17], v[150:153], v[146:149], v[2:17]
	global_load_dwordx4 v[66:69], v210, s[0:1] offset:512
	global_load_dwordx4 v[70:73], v210, s[2:3] offset:512
	global_load_dwordx4 v[74:77], v214, s[4:5] offset:512
	global_load_dwordx4 v[78:81], v214, s[6:7] offset:512
	ds_read_b128 v[130:133], v219 offset:36864
	ds_read_b128 v[134:137], v220 offset:36864
	ds_read_b128 v[138:141], v219 offset:41472
	s_waitcnt lgkmcnt(11)
	v_mfma_f32_32x32x16_bf16 v[18:33], v[154:157], v[158:161], v[18:33]
	ds_read_b128 v[142:145], v219 offset:36896
	ds_read_b128 v[146:149], v220 offset:36896
	ds_read_b128 v[150:153], v219 offset:41504
	s_waitcnt lgkmcnt(13)
	v_mfma_f32_32x32x16_bf16 v[2:17], v[162:165], v[158:161], v[2:17]
	s_waitcnt lgkmcnt(11)
	v_mfma_f32_32x32x16_bf16 v[18:33], v[166:169], v[170:173], v[18:33]
	s_waitcnt lgkmcnt(10)
	v_mfma_f32_32x32x16_bf16 v[2:17], v[174:177], v[170:173], v[2:17]
	s_waitcnt lgkmcnt(0)
	s_barrier
; DI float bflo(unsigned w) { return __uint_as_float(w << 16); }
; DI float bfhi(unsigned w) { return __uint_as_float(w & 0xffff0000u); }
; DI int tidx() { int t = threadIdx.x; asm volatile("" : "+v"(t)); return t; }
; template <class ACC>
; DI void merge_branch(const Prm& p, u16* smem, const u16* W, const u16* X, int ld, int bi, int n0, int m0, ACC& macc) {
;     ...
;   auto epi = [&](f32x16 (&acc)[2], int wm, int wn, int lane) __attribute__((always_inline)) {
;     const int lr = lane & 31, lh = lane >> 5;
;     const int tok = m0 + wn * 32 + lr;
; #pragma unroll
;     for (int i = 0; i < 2; ++i)
; #pragma unroll
;       for (int h2 = 0; h2 < 2; ++h2) {
;         const int n = n0 + wm * 64 + i * 32 + 16 * lh + 8 * h2;
;         const u32x4 gz = *(const u32x4*)(p.zg + (size_t)tok * 4096 + bi * 1024 + n);
; #pragma unroll
;         for (int e = 0; e < 4; ++e) {
;           macc[i][8 * h2 + 2 * e] += bflo(gz[e]) * acc[i][8 * h2 + 2 * e];
;           macc[i][8 * h2 + 2 * e + 1] += bfhi(gz[e]) * acc[i][8 * h2 + 2 * e + 1];
;         }
; DI void phase_merge(const Prm& p, u16* smem, int l, int& base) {
;     ...
;     const int tid2 = tidx(), lane = tid2 & 63, wave = tid2 >> 6, wm = wave >> 2, wn = wave & 3, lr = lane & 31, lh = lane >> 5;
;     const int tok = m0 + wn * 32 + lr;
; #pragma unroll
;     for (int i = 0; i < 2; ++i)
; #pragma unroll
;       for (int h2 = 0; h2 < 2; ++h2) {
;         u32x4 o;
; #pragma unroll
;         for (int e = 0; e < 4; ++e) o[e] = pack2(macc[i][8 * h2 + 2 * e], macc[i][8 * h2 + 2 * e + 1]);
;         *(u32x4*)(p.hbuf + (size_t)tok * 1024 + n0 + wm * 64 + i * 32 + 16 * lh + 8 * h2) = o;
;       }
	ds_read_b128 v[154:157], v219 offset:36928
	ds_read_b128 v[158:161], v220 offset:36928
	ds_read_b128 v[162:165], v219 offset:41536
	v_mfma_f32_32x32x16_bf16 v[18:33], v[130:133], v[134:137], v[18:33]
	ds_read_b128 v[166:169], v219 offset:36960
	ds_read_b128 v[170:173], v220 offset:36960
	ds_read_b128 v[174:177], v219 offset:41568
	v_mfma_f32_32x32x16_bf16 v[2:17], v[138:141], v[134:137], v[2:17]
	s_waitcnt vmcnt(12)
	ds_write_b128 v218, v[82:85] offset:18432
	ds_write_b128 v218, v[86:89] offset:27648
	v_mfma_f32_32x32x16_bf16 v[18:33], v[142:145], v[146:149], v[18:33]
	ds_write_b128 v223, v[90:93] offset:18432
	ds_write_b128 v223, v[94:97] offset:27648
	v_mfma_f32_32x32x16_bf16 v[2:17], v[150:153], v[146:149], v[2:17]
	global_load_dwordx4 v[82:85], v210, s[0:1] offset:640
	global_load_dwordx4 v[86:89], v210, s[2:3] offset:640
	global_load_dwordx4 v[90:93], v214, s[4:5] offset:640
	global_load_dwordx4 v[94:97], v214, s[6:7] offset:640
	ds_read_b128 v[130:133], v219
	ds_read_b128 v[134:137], v220
	ds_read_b128 v[138:141], v219 offset:4608
	s_waitcnt lgkmcnt(11)
	v_mfma_f32_32x32x16_bf16 v[18:33], v[154:157], v[158:161], v[18:33]
	ds_read_b128 v[142:145], v219 offset:32
	ds_read_b128 v[146:149], v220 offset:32
	ds_read_b128 v[150:153], v219 offset:4640
	s_waitcnt lgkmcnt(13)
	v_mfma_f32_32x32x16_bf16 v[2:17], v[162:165], v[158:161], v[2:17]
	s_waitcnt lgkmcnt(11)
	v_mfma_f32_32x32x16_bf16 v[18:33], v[166:169], v[170:173], v[18:33]
	s_waitcnt lgkmcnt(10)
	v_mfma_f32_32x32x16_bf16 v[2:17], v[174:177], v[170:173], v[2:17]
	s_waitcnt vmcnt(36)
	s_nop 15
	v_lshlrev_b32_e32 v226, 16, v194
	v_and_b32_e32 v227, 0xffff0000, v194
	v_pk_fma_f32 v[34:35], v[226:227], v[18:19], v[34:35]
	v_lshlrev_b32_e32 v228, 16, v195
	v_and_b32_e32 v229, 0xffff0000, v195
	v_pk_fma_f32 v[36:37], v[228:229], v[20:21], v[36:37]
	v_lshlrev_b32_e32 v234, 16, v196
	v_and_b32_e32 v235, 0xffff0000, v196
	v_pk_fma_f32 v[38:39], v[234:235], v[22:23], v[38:39]
	v_lshlrev_b32_e32 v236, 16, v197
	v_and_b32_e32 v237, 0xffff0000, v197
	v_pk_fma_f32 v[40:41], v[236:237], v[24:25], v[40:41]
	v_lshlrev_b32_e32 v226, 16, v198
	v_and_b32_e32 v227, 0xffff0000, v198
	v_pk_fma_f32 v[42:43], v[226:227], v[26:27], v[42:43]
	v_lshlrev_b32_e32 v228, 16, v199
	v_and_b32_e32 v229, 0xffff0000, v199
	v_pk_fma_f32 v[44:45], v[228:229], v[28:29], v[44:45]
	v_lshlrev_b32_e32 v234, 16, v200
	v_and_b32_e32 v235, 0xffff0000, v200
	v_pk_fma_f32 v[46:47], v[234:235], v[30:31], v[46:47]
	v_lshlrev_b32_e32 v236, 16, v201
	v_and_b32_e32 v237, 0xffff0000, v201
	v_pk_fma_f32 v[48:49], v[236:237], v[32:33], v[48:49]
	v_lshlrev_b32_e32 v226, 16, v202
	v_and_b32_e32 v227, 0xffff0000, v202
	v_pk_fma_f32 v[50:51], v[226:227], v[2:3], v[50:51]
	v_lshlrev_b32_e32 v228, 16, v203
	v_and_b32_e32 v229, 0xffff0000, v203
	v_pk_fma_f32 v[52:53], v[228:229], v[4:5], v[52:53]
	v_lshlrev_b32_e32 v234, 16, v204
	v_and_b32_e32 v235, 0xffff0000, v204
	v_pk_fma_f32 v[54:55], v[234:235], v[6:7], v[54:55]
	v_lshlrev_b32_e32 v236, 16, v205
	v_and_b32_e32 v237, 0xffff0000, v205
	v_pk_fma_f32 v[56:57], v[236:237], v[8:9], v[56:57]
	v_lshlrev_b32_e32 v226, 16, v206
	v_and_b32_e32 v227, 0xffff0000, v206
	v_pk_fma_f32 v[58:59], v[226:227], v[10:11], v[58:59]
	v_lshlrev_b32_e32 v228, 16, v207
	v_and_b32_e32 v229, 0xffff0000, v207
	v_pk_fma_f32 v[60:61], v[228:229], v[12:13], v[60:61]
	v_lshlrev_b32_e32 v234, 16, v208
	v_and_b32_e32 v235, 0xffff0000, v208
	v_pk_fma_f32 v[62:63], v[234:235], v[14:15], v[62:63]
	v_lshlrev_b32_e32 v236, 16, v209
	v_and_b32_e32 v237, 0xffff0000, v209
	v_pk_fma_f32 v[64:65], v[236:237], v[16:17], v[64:65]
	v_cvt_pk_bf16_f32 v178, v34, v35
	v_cvt_pk_bf16_f32 v179, v36, v37
	v_cvt_pk_bf16_f32 v180, v38, v39
	v_cvt_pk_bf16_f32 v181, v40, v41
	v_cvt_pk_bf16_f32 v182, v42, v43
	v_cvt_pk_bf16_f32 v183, v44, v45
	v_cvt_pk_bf16_f32 v184, v46, v47
	v_cvt_pk_bf16_f32 v185, v48, v49
	v_cvt_pk_bf16_f32 v186, v50, v51
	v_cvt_pk_bf16_f32 v187, v52, v53
	v_cvt_pk_bf16_f32 v188, v54, v55
	v_cvt_pk_bf16_f32 v189, v56, v57
	v_cvt_pk_bf16_f32 v190, v58, v59
	v_cvt_pk_bf16_f32 v191, v60, v61
	v_cvt_pk_bf16_f32 v192, v62, v63
	v_cvt_pk_bf16_f32 v193, v64, v65
	global_store_dwordx4 v222, v[178:181], s[12:13]
	global_store_dwordx4 v222, v[182:185], s[12:13] offset:16
	global_store_dwordx4 v222, v[186:189], s[12:13] offset:64
	global_store_dwordx4 v222, v[190:193], s[12:13] offset:80
	s_waitcnt lgkmcnt(0)
	s_barrier
	s_add_i32 s31, s31, s30
	s_mov_b32 s58, s60
	s_mov_b32 s59, s61
	s_cmpk_lt_i32 s31, 0x400
	s_cbranch_scc1 .Lmrg_task
